# x14 + GLA state scan (G2) rewritten straight-line with U/decay loads 8 steps ahead (counted vmcnt), same arithmetic
# speedup vs baseline: 1.0100x; 1.0069x over previous
; __device__ __forceinline__ unsigned cvt_pk_bf16(float lo, float hi) { unsigned r; asm volatile("v_cvt_pk_bf16_f32 %0, %1, %2" : "=v"(r) : "v"(lo), "v"(hi)); return r; }
; __device__ __forceinline__ void gla_g2(const Params& P, int tid, int G, int bid) {
;     const float* U = (const float*)(P.ws + WS_GU); const float* Dv = (const float*)(P.ws + WS_GD); bf16_t* S = (bf16_t*)(P.ws + WS_GS);
;     for (int slot = bid * 512 + tid; slot < 16 * 8192; slot += G * 512) {
;         const int seq = slot >> 13, el = (slot & 8191) * 2, d = el & 127, dir = seq & 1;
;         float s0 = 0.f, s1 = 0.f;
; #pragma unroll 17
;         for (int p = 0; p < NCH; ++p) {
;             const int id = dir == 0 ? p : (p < 4 ? 3 - p : 71 - p);
;             const size_t base = ((size_t)seq * NCH + id);
;             *(unsigned*)(S + base * 16384 + el) = cvt_pk_bf16(s0, s1);
;             const f32x2 u = *(const f32x2*)(U + base * 16384 + el), dd = *(const f32x2*)(Dv + base * 128 + d);
;             s0 = dd.x * s0 + u.x; s1 = dd.y * s1 + u.y;
;         }
;     }
; }
.LBB0_829:
	v_lshlrev_b32_e32 v1, 1, v10
	v_and_b32_e32 v2, 0x3ffe, v1
	v_ashrrev_i32_e32 v0, 13, v10
	v_and_b32_e32 v1, 0x2000, v10
	v_lshlrev_b32_e32 v96, 1, v2
	v_cmp_eq_u32_e32 vcc, 0, v1
	v_mul_i32_i24_e32 v11, 0x44, v0
	v_lshl_add_u64 v[0:1], s[48:49], 0, v[96:97]
	v_lshlrev_b32_e32 v96, 2, v2
	v_lshlrev_b32_e32 v4, 3, v10
	v_lshl_add_u64 v[2:3], s[44:45], 0, v[96:97]
	v_and_b32_e32 v96, 0x1f8, v4
	v_mov_b32_e32 v6, 0
	s_mov_b32 s17, 0
	v_lshl_add_u64 v[4:5], s[46:47], 0, v[96:97]
	s_mov_b32 s18, 55
	v_mov_b32_e32 v7, v6
	v_cndmask_b32_e32 v12, 3, v97, vcc
	v_add_u32_e32 v12, v12, v11
	v_mov_b32_e32 v13, v97
	v_lshlrev_b64 v[100:101], 16, v[12:13]
	v_lshlrev_b64 v[102:103], 9, v[12:13]
	v_lshlrev_b64 v[104:105], 15, v[12:13]
	v_lshl_add_u64 v[100:101], v[2:3], 0, v[100:101]
	v_lshl_add_u64 v[102:103], v[4:5], 0, v[102:103]
	v_lshl_add_u64 v[104:105], v[0:1], 0, v[104:105]
	v_mov_b32_e32 v106, 0x10000
	v_mov_b32_e32 v14, 0xffff0000
	v_cndmask_b32_e32 v106, v14, v106, vcc
	v_cndmask_b32_e32 v107, -1, v97, vcc
	v_mov_b32_e32 v108, 0x200
	v_mov_b32_e32 v14, 0xfffffe00
	v_cndmask_b32_e32 v108, v14, v108, vcc
	v_cndmask_b32_e32 v109, -1, v97, vcc
	v_mov_b32_e32 v110, 0x8000
	v_mov_b32_e32 v14, 0xffff8000
	v_cndmask_b32_e32 v110, v14, v110, vcc
	v_cndmask_b32_e32 v111, -1, v97, vcc
	v_mov_b32_e32 v112, 0x10000
	v_mov_b32_e32 v14, 0x430000
	v_cndmask_b32_e32 v112, v14, v112, vcc
	v_cndmask_b32_e32 v113, 0, v97, vcc
	v_mov_b32_e32 v114, 0x200
	v_mov_b32_e32 v14, 0x8600
	v_cndmask_b32_e32 v114, v14, v114, vcc
	v_cndmask_b32_e32 v115, 0, v97, vcc
	v_mov_b32_e32 v116, 0x8000
	v_mov_b32_e32 v14, 0x218000
	v_cndmask_b32_e32 v116, v14, v116, vcc
	v_cndmask_b32_e32 v117, 0, v97, vcc
	global_load_dwordx2 v[120:121], v[100:101], off
	global_load_dwordx2 v[122:123], v[102:103], off
	v_lshl_add_u64 v[100:101], v[100:101], 0, v[106:107]
	v_lshl_add_u64 v[102:103], v[102:103], 0, v[108:109]
	global_load_dwordx2 v[124:125], v[100:101], off
	global_load_dwordx2 v[126:127], v[102:103], off
	v_lshl_add_u64 v[100:101], v[100:101], 0, v[106:107]
	v_lshl_add_u64 v[102:103], v[102:103], 0, v[108:109]
	global_load_dwordx2 v[128:129], v[100:101], off
	global_load_dwordx2 v[130:131], v[102:103], off
	v_lshl_add_u64 v[100:101], v[100:101], 0, v[106:107]
	v_lshl_add_u64 v[102:103], v[102:103], 0, v[108:109]
	global_load_dwordx2 v[132:133], v[100:101], off
	global_load_dwordx2 v[134:135], v[102:103], off
	v_lshl_add_u64 v[100:101], v[100:101], 0, v[112:113]
	v_lshl_add_u64 v[102:103], v[102:103], 0, v[114:115]
	global_load_dwordx2 v[136:137], v[100:101], off
	global_load_dwordx2 v[138:139], v[102:103], off
	v_lshl_add_u64 v[100:101], v[100:101], 0, v[106:107]
	v_lshl_add_u64 v[102:103], v[102:103], 0, v[108:109]
	global_load_dwordx2 v[140:141], v[100:101], off
	global_load_dwordx2 v[142:143], v[102:103], off
	v_lshl_add_u64 v[100:101], v[100:101], 0, v[106:107]
	v_lshl_add_u64 v[102:103], v[102:103], 0, v[108:109]
	global_load_dwordx2 v[144:145], v[100:101], off
	global_load_dwordx2 v[146:147], v[102:103], off
	v_lshl_add_u64 v[100:101], v[100:101], 0, v[106:107]
	v_lshl_add_u64 v[102:103], v[102:103], 0, v[108:109]
	global_load_dwordx2 v[148:149], v[100:101], off
	global_load_dwordx2 v[150:151], v[102:103], off
	v_lshl_add_u64 v[100:101], v[100:101], 0, v[106:107]
	v_lshl_add_u64 v[102:103], v[102:103], 0, v[108:109]
	v_cvt_pk_bf16_f32 v16, v6, v7
	global_store_dword v[104:105], v16, off
	v_lshl_add_u64 v[104:105], v[104:105], 0, v[110:111]
	s_waitcnt vmcnt(15)
	v_pk_fma_f32 v[6:7], v[6:7], v[122:123], v[120:121]
	global_load_dwordx2 v[120:121], v[100:101], off
	global_load_dwordx2 v[122:123], v[102:103], off
	v_lshl_add_u64 v[100:101], v[100:101], 0, v[106:107]
	v_lshl_add_u64 v[102:103], v[102:103], 0, v[108:109]
	v_cvt_pk_bf16_f32 v16, v6, v7
	global_store_dword v[104:105], v16, off
	v_lshl_add_u64 v[104:105], v[104:105], 0, v[110:111]
	s_waitcnt vmcnt(16)
	v_pk_fma_f32 v[6:7], v[6:7], v[126:127], v[124:125]
	global_load_dwordx2 v[124:125], v[100:101], off
	global_load_dwordx2 v[126:127], v[102:103], off
	v_lshl_add_u64 v[100:101], v[100:101], 0, v[106:107]
	v_lshl_add_u64 v[102:103], v[102:103], 0, v[108:109]
	v_cvt_pk_bf16_f32 v16, v6, v7
	global_store_dword v[104:105], v16, off
	v_lshl_add_u64 v[104:105], v[104:105], 0, v[110:111]
	s_waitcnt vmcnt(17)
	v_pk_fma_f32 v[6:7], v[6:7], v[130:131], v[128:129]
	global_load_dwordx2 v[128:129], v[100:101], off
	global_load_dwordx2 v[130:131], v[102:103], off
	v_lshl_add_u64 v[100:101], v[100:101], 0, v[106:107]
	v_lshl_add_u64 v[102:103], v[102:103], 0, v[108:109]
	v_cvt_pk_bf16_f32 v16, v6, v7
	global_store_dword v[104:105], v16, off
	v_lshl_add_u64 v[104:105], v[104:105], 0, v[116:117]
	s_waitcnt vmcnt(18)
	v_pk_fma_f32 v[6:7], v[6:7], v[134:135], v[132:133]
	global_load_dwordx2 v[132:133], v[100:101], off
	global_load_dwordx2 v[134:135], v[102:103], off
	v_lshl_add_u64 v[100:101], v[100:101], 0, v[106:107]
	v_lshl_add_u64 v[102:103], v[102:103], 0, v[108:109]
	v_cvt_pk_bf16_f32 v16, v6, v7
	global_store_dword v[104:105], v16, off
	v_lshl_add_u64 v[104:105], v[104:105], 0, v[110:111]
	s_waitcnt vmcnt(19)
	v_pk_fma_f32 v[6:7], v[6:7], v[138:139], v[136:137]
	global_load_dwordx2 v[136:137], v[100:101], off
	global_load_dwordx2 v[138:139], v[102:103], off
	v_lshl_add_u64 v[100:101], v[100:101], 0, v[106:107]
	v_lshl_add_u64 v[102:103], v[102:103], 0, v[108:109]
	v_cvt_pk_bf16_f32 v16, v6, v7
	global_store_dword v[104:105], v16, off
	v_lshl_add_u64 v[104:105], v[104:105], 0, v[110:111]
	s_waitcnt vmcnt(20)
; __device__ __forceinline__ unsigned cvt_pk_bf16(float lo, float hi) { unsigned r; asm volatile("v_cvt_pk_bf16_f32 %0, %1, %2" : "=v"(r) : "v"(lo), "v"(hi)); return r; }
; __device__ __forceinline__ void gla_g2(const Params& P, int tid, int G, int bid) {
;     const float* U = (const float*)(P.ws + WS_GU); const float* Dv = (const float*)(P.ws + WS_GD); bf16_t* S = (bf16_t*)(P.ws + WS_GS);
;     for (int slot = bid * 512 + tid; slot < 16 * 8192; slot += G * 512) {
;         const int seq = slot >> 13, el = (slot & 8191) * 2, d = el & 127, dir = seq & 1;
;         float s0 = 0.f, s1 = 0.f;
; #pragma unroll 17
;         for (int p = 0; p < NCH; ++p) {
;             const int id = dir == 0 ? p : (p < 4 ? 3 - p : 71 - p);
;             const size_t base = ((size_t)seq * NCH + id);
;             *(unsigned*)(S + base * 16384 + el) = cvt_pk_bf16(s0, s1);
;             const f32x2 u = *(const f32x2*)(U + base * 16384 + el), dd = *(const f32x2*)(Dv + base * 128 + d);
;             s0 = dd.x * s0 + u.x; s1 = dd.y * s1 + u.y;
;         }
;     }
; }
	v_pk_fma_f32 v[6:7], v[6:7], v[142:143], v[140:141]
	global_load_dwordx2 v[140:141], v[100:101], off
	global_load_dwordx2 v[142:143], v[102:103], off
	v_lshl_add_u64 v[100:101], v[100:101], 0, v[106:107]
	v_lshl_add_u64 v[102:103], v[102:103], 0, v[108:109]
	v_cvt_pk_bf16_f32 v16, v6, v7
	global_store_dword v[104:105], v16, off
	v_lshl_add_u64 v[104:105], v[104:105], 0, v[110:111]
	s_waitcnt vmcnt(21)
	v_pk_fma_f32 v[6:7], v[6:7], v[146:147], v[144:145]
	global_load_dwordx2 v[144:145], v[100:101], off
	global_load_dwordx2 v[146:147], v[102:103], off
	v_lshl_add_u64 v[100:101], v[100:101], 0, v[106:107]
	v_lshl_add_u64 v[102:103], v[102:103], 0, v[108:109]
	v_cvt_pk_bf16_f32 v16, v6, v7
	global_store_dword v[104:105], v16, off
	v_lshl_add_u64 v[104:105], v[104:105], 0, v[110:111]
	s_waitcnt vmcnt(22)
	v_pk_fma_f32 v[6:7], v[6:7], v[150:151], v[148:149]
	global_load_dwordx2 v[148:149], v[100:101], off
	global_load_dwordx2 v[150:151], v[102:103], off
	v_lshl_add_u64 v[100:101], v[100:101], 0, v[106:107]
	v_lshl_add_u64 v[102:103], v[102:103], 0, v[108:109]
	v_cvt_pk_bf16_f32 v16, v6, v7
	global_store_dword v[104:105], v16, off
	v_lshl_add_u64 v[104:105], v[104:105], 0, v[110:111]
	s_waitcnt vmcnt(22)
	v_pk_fma_f32 v[6:7], v[6:7], v[122:123], v[120:121]
	global_load_dwordx2 v[120:121], v[100:101], off
	global_load_dwordx2 v[122:123], v[102:103], off
	v_lshl_add_u64 v[100:101], v[100:101], 0, v[106:107]
	v_lshl_add_u64 v[102:103], v[102:103], 0, v[108:109]
	v_cvt_pk_bf16_f32 v16, v6, v7
	global_store_dword v[104:105], v16, off
	v_lshl_add_u64 v[104:105], v[104:105], 0, v[110:111]
	s_waitcnt vmcnt(22)
	v_pk_fma_f32 v[6:7], v[6:7], v[126:127], v[124:125]
	global_load_dwordx2 v[124:125], v[100:101], off
	global_load_dwordx2 v[126:127], v[102:103], off
	v_lshl_add_u64 v[100:101], v[100:101], 0, v[106:107]
	v_lshl_add_u64 v[102:103], v[102:103], 0, v[108:109]
	v_cvt_pk_bf16_f32 v16, v6, v7
	global_store_dword v[104:105], v16, off
	v_lshl_add_u64 v[104:105], v[104:105], 0, v[110:111]
	s_waitcnt vmcnt(22)
	v_pk_fma_f32 v[6:7], v[6:7], v[130:131], v[128:129]
	global_load_dwordx2 v[128:129], v[100:101], off
	global_load_dwordx2 v[130:131], v[102:103], off
	v_lshl_add_u64 v[100:101], v[100:101], 0, v[106:107]
	v_lshl_add_u64 v[102:103], v[102:103], 0, v[108:109]
	v_cvt_pk_bf16_f32 v16, v6, v7
	global_store_dword v[104:105], v16, off
	v_lshl_add_u64 v[104:105], v[104:105], 0, v[110:111]
	s_waitcnt vmcnt(22)
	v_pk_fma_f32 v[6:7], v[6:7], v[134:135], v[132:133]
	global_load_dwordx2 v[132:133], v[100:101], off
	global_load_dwordx2 v[134:135], v[102:103], off
	v_lshl_add_u64 v[100:101], v[100:101], 0, v[106:107]
	v_lshl_add_u64 v[102:103], v[102:103], 0, v[108:109]
	v_cvt_pk_bf16_f32 v16, v6, v7
	global_store_dword v[104:105], v16, off
	v_lshl_add_u64 v[104:105], v[104:105], 0, v[110:111]
	s_waitcnt vmcnt(22)
	v_pk_fma_f32 v[6:7], v[6:7], v[138:139], v[136:137]
	global_load_dwordx2 v[136:137], v[100:101], off
	global_load_dwordx2 v[138:139], v[102:103], off
	v_lshl_add_u64 v[100:101], v[100:101], 0, v[106:107]
	v_lshl_add_u64 v[102:103], v[102:103], 0, v[108:109]
	v_cvt_pk_bf16_f32 v16, v6, v7
	global_store_dword v[104:105], v16, off
	v_lshl_add_u64 v[104:105], v[104:105], 0, v[110:111]
	s_waitcnt vmcnt(22)
	v_pk_fma_f32 v[6:7], v[6:7], v[142:143], v[140:141]
	global_load_dwordx2 v[140:141], v[100:101], off
	global_load_dwordx2 v[142:143], v[102:103], off
	v_lshl_add_u64 v[100:101], v[100:101], 0, v[106:107]
	v_lshl_add_u64 v[102:103], v[102:103], 0, v[108:109]
	v_cvt_pk_bf16_f32 v16, v6, v7
	global_store_dword v[104:105], v16, off
	v_lshl_add_u64 v[104:105], v[104:105], 0, v[110:111]
	s_waitcnt vmcnt(22)
	v_pk_fma_f32 v[6:7], v[6:7], v[146:147], v[144:145]
	global_load_dwordx2 v[144:145], v[100:101], off
	global_load_dwordx2 v[146:147], v[102:103], off
	v_lshl_add_u64 v[100:101], v[100:101], 0, v[106:107]
	v_lshl_add_u64 v[102:103], v[102:103], 0, v[108:109]
	v_cvt_pk_bf16_f32 v16, v6, v7
	global_store_dword v[104:105], v16, off
	v_lshl_add_u64 v[104:105], v[104:105], 0, v[110:111]
	s_waitcnt vmcnt(22)
	v_pk_fma_f32 v[6:7], v[6:7], v[150:151], v[148:149]
	global_load_dwordx2 v[148:149], v[100:101], off
	global_load_dwordx2 v[150:151], v[102:103], off
	v_lshl_add_u64 v[100:101], v[100:101], 0, v[106:107]
	v_lshl_add_u64 v[102:103], v[102:103], 0, v[108:109]
	v_cvt_pk_bf16_f32 v16, v6, v7
	global_store_dword v[104:105], v16, off
	v_lshl_add_u64 v[104:105], v[104:105], 0, v[110:111]
	s_waitcnt vmcnt(22)
	v_pk_fma_f32 v[6:7], v[6:7], v[122:123], v[120:121]
	global_load_dwordx2 v[120:121], v[100:101], off
	global_load_dwordx2 v[122:123], v[102:103], off
	v_lshl_add_u64 v[100:101], v[100:101], 0, v[106:107]
	v_lshl_add_u64 v[102:103], v[102:103], 0, v[108:109]
	v_cvt_pk_bf16_f32 v16, v6, v7
	global_store_dword v[104:105], v16, off
	v_lshl_add_u64 v[104:105], v[104:105], 0, v[110:111]
	s_waitcnt vmcnt(22)
	v_pk_fma_f32 v[6:7], v[6:7], v[126:127], v[124:125]
	global_load_dwordx2 v[124:125], v[100:101], off
	global_load_dwordx2 v[126:127], v[102:103], off
	v_lshl_add_u64 v[100:101], v[100:101], 0, v[106:107]
	v_lshl_add_u64 v[102:103], v[102:103], 0, v[108:109]
	v_cvt_pk_bf16_f32 v16, v6, v7
	global_store_dword v[104:105], v16, off
	v_lshl_add_u64 v[104:105], v[104:105], 0, v[110:111]
	s_waitcnt vmcnt(22)
	v_pk_fma_f32 v[6:7], v[6:7], v[130:131], v[128:129]
	global_load_dwordx2 v[128:129], v[100:101], off
	global_load_dwordx2 v[130:131], v[102:103], off
	v_lshl_add_u64 v[100:101], v[100:101], 0, v[106:107]
	v_lshl_add_u64 v[102:103], v[102:103], 0, v[108:109]
	v_cvt_pk_bf16_f32 v16, v6, v7
	global_store_dword v[104:105], v16, off
	v_lshl_add_u64 v[104:105], v[104:105], 0, v[110:111]
	s_waitcnt vmcnt(22)
; __device__ __forceinline__ unsigned cvt_pk_bf16(float lo, float hi) { unsigned r; asm volatile("v_cvt_pk_bf16_f32 %0, %1, %2" : "=v"(r) : "v"(lo), "v"(hi)); return r; }
; __device__ __forceinline__ void gla_g2(const Params& P, int tid, int G, int bid) {
;     const float* U = (const float*)(P.ws + WS_GU); const float* Dv = (const float*)(P.ws + WS_GD); bf16_t* S = (bf16_t*)(P.ws + WS_GS);
;     for (int slot = bid * 512 + tid; slot < 16 * 8192; slot += G * 512) {
;         const int seq = slot >> 13, el = (slot & 8191) * 2, d = el & 127, dir = seq & 1;
;         float s0 = 0.f, s1 = 0.f;
; #pragma unroll 17
;         for (int p = 0; p < NCH; ++p) {
;             const int id = dir == 0 ? p : (p < 4 ? 3 - p : 71 - p);
;             const size_t base = ((size_t)seq * NCH + id);
;             *(unsigned*)(S + base * 16384 + el) = cvt_pk_bf16(s0, s1);
;             const f32x2 u = *(const f32x2*)(U + base * 16384 + el), dd = *(const f32x2*)(Dv + base * 128 + d);
;             s0 = dd.x * s0 + u.x; s1 = dd.y * s1 + u.y;
;         }
;     }
; }
	v_pk_fma_f32 v[6:7], v[6:7], v[134:135], v[132:133]
	global_load_dwordx2 v[132:133], v[100:101], off
	global_load_dwordx2 v[134:135], v[102:103], off
	v_lshl_add_u64 v[100:101], v[100:101], 0, v[106:107]
	v_lshl_add_u64 v[102:103], v[102:103], 0, v[108:109]
	v_cvt_pk_bf16_f32 v16, v6, v7
	global_store_dword v[104:105], v16, off
	v_lshl_add_u64 v[104:105], v[104:105], 0, v[110:111]
	s_waitcnt vmcnt(22)
	v_pk_fma_f32 v[6:7], v[6:7], v[138:139], v[136:137]
	global_load_dwordx2 v[136:137], v[100:101], off
	global_load_dwordx2 v[138:139], v[102:103], off
	v_lshl_add_u64 v[100:101], v[100:101], 0, v[106:107]
	v_lshl_add_u64 v[102:103], v[102:103], 0, v[108:109]
	v_cvt_pk_bf16_f32 v16, v6, v7
	global_store_dword v[104:105], v16, off
	v_lshl_add_u64 v[104:105], v[104:105], 0, v[110:111]
	s_waitcnt vmcnt(22)
	v_pk_fma_f32 v[6:7], v[6:7], v[142:143], v[140:141]
	global_load_dwordx2 v[140:141], v[100:101], off
	global_load_dwordx2 v[142:143], v[102:103], off
	v_lshl_add_u64 v[100:101], v[100:101], 0, v[106:107]
	v_lshl_add_u64 v[102:103], v[102:103], 0, v[108:109]
	v_cvt_pk_bf16_f32 v16, v6, v7
	global_store_dword v[104:105], v16, off
	v_lshl_add_u64 v[104:105], v[104:105], 0, v[110:111]
	s_waitcnt vmcnt(22)
	v_pk_fma_f32 v[6:7], v[6:7], v[146:147], v[144:145]
	global_load_dwordx2 v[144:145], v[100:101], off
	global_load_dwordx2 v[146:147], v[102:103], off
	v_lshl_add_u64 v[100:101], v[100:101], 0, v[106:107]
	v_lshl_add_u64 v[102:103], v[102:103], 0, v[108:109]
	v_cvt_pk_bf16_f32 v16, v6, v7
	global_store_dword v[104:105], v16, off
	v_lshl_add_u64 v[104:105], v[104:105], 0, v[110:111]
	s_waitcnt vmcnt(22)
	v_pk_fma_f32 v[6:7], v[6:7], v[150:151], v[148:149]
	global_load_dwordx2 v[148:149], v[100:101], off
	global_load_dwordx2 v[150:151], v[102:103], off
	v_lshl_add_u64 v[100:101], v[100:101], 0, v[106:107]
	v_lshl_add_u64 v[102:103], v[102:103], 0, v[108:109]
	v_cvt_pk_bf16_f32 v16, v6, v7
	global_store_dword v[104:105], v16, off
	v_lshl_add_u64 v[104:105], v[104:105], 0, v[110:111]
	s_waitcnt vmcnt(22)
	v_pk_fma_f32 v[6:7], v[6:7], v[122:123], v[120:121]
	global_load_dwordx2 v[120:121], v[100:101], off
	global_load_dwordx2 v[122:123], v[102:103], off
	v_lshl_add_u64 v[100:101], v[100:101], 0, v[106:107]
	v_lshl_add_u64 v[102:103], v[102:103], 0, v[108:109]
	v_cvt_pk_bf16_f32 v16, v6, v7
	global_store_dword v[104:105], v16, off
	v_lshl_add_u64 v[104:105], v[104:105], 0, v[110:111]
	s_waitcnt vmcnt(22)
	v_pk_fma_f32 v[6:7], v[6:7], v[126:127], v[124:125]
	global_load_dwordx2 v[124:125], v[100:101], off
	global_load_dwordx2 v[126:127], v[102:103], off
	v_lshl_add_u64 v[100:101], v[100:101], 0, v[106:107]
	v_lshl_add_u64 v[102:103], v[102:103], 0, v[108:109]
	v_cvt_pk_bf16_f32 v16, v6, v7
	global_store_dword v[104:105], v16, off
	v_lshl_add_u64 v[104:105], v[104:105], 0, v[110:111]
	s_waitcnt vmcnt(22)
	v_pk_fma_f32 v[6:7], v[6:7], v[130:131], v[128:129]
	global_load_dwordx2 v[128:129], v[100:101], off
	global_load_dwordx2 v[130:131], v[102:103], off
	v_lshl_add_u64 v[100:101], v[100:101], 0, v[106:107]
	v_lshl_add_u64 v[102:103], v[102:103], 0, v[108:109]
	v_cvt_pk_bf16_f32 v16, v6, v7
	global_store_dword v[104:105], v16, off
	v_lshl_add_u64 v[104:105], v[104:105], 0, v[110:111]
	s_waitcnt vmcnt(22)
	v_pk_fma_f32 v[6:7], v[6:7], v[134:135], v[132:133]
	global_load_dwordx2 v[132:133], v[100:101], off
	global_load_dwordx2 v[134:135], v[102:103], off
	v_lshl_add_u64 v[100:101], v[100:101], 0, v[106:107]
	v_lshl_add_u64 v[102:103], v[102:103], 0, v[108:109]
	v_cvt_pk_bf16_f32 v16, v6, v7
	global_store_dword v[104:105], v16, off
	v_lshl_add_u64 v[104:105], v[104:105], 0, v[110:111]
	s_waitcnt vmcnt(22)
	v_pk_fma_f32 v[6:7], v[6:7], v[138:139], v[136:137]
	global_load_dwordx2 v[136:137], v[100:101], off
	global_load_dwordx2 v[138:139], v[102:103], off
	v_lshl_add_u64 v[100:101], v[100:101], 0, v[106:107]
	v_lshl_add_u64 v[102:103], v[102:103], 0, v[108:109]
	v_cvt_pk_bf16_f32 v16, v6, v7
	global_store_dword v[104:105], v16, off
	v_lshl_add_u64 v[104:105], v[104:105], 0, v[110:111]
	s_waitcnt vmcnt(22)
	v_pk_fma_f32 v[6:7], v[6:7], v[142:143], v[140:141]
	global_load_dwordx2 v[140:141], v[100:101], off
	global_load_dwordx2 v[142:143], v[102:103], off
	v_lshl_add_u64 v[100:101], v[100:101], 0, v[106:107]
	v_lshl_add_u64 v[102:103], v[102:103], 0, v[108:109]
	v_cvt_pk_bf16_f32 v16, v6, v7
	global_store_dword v[104:105], v16, off
	v_lshl_add_u64 v[104:105], v[104:105], 0, v[110:111]
	s_waitcnt vmcnt(22)
	v_pk_fma_f32 v[6:7], v[6:7], v[146:147], v[144:145]
	global_load_dwordx2 v[144:145], v[100:101], off
	global_load_dwordx2 v[146:147], v[102:103], off
	v_lshl_add_u64 v[100:101], v[100:101], 0, v[106:107]
	v_lshl_add_u64 v[102:103], v[102:103], 0, v[108:109]
	v_cvt_pk_bf16_f32 v16, v6, v7
	global_store_dword v[104:105], v16, off
	v_lshl_add_u64 v[104:105], v[104:105], 0, v[110:111]
	s_waitcnt vmcnt(22)
	v_pk_fma_f32 v[6:7], v[6:7], v[150:151], v[148:149]
	global_load_dwordx2 v[148:149], v[100:101], off
	global_load_dwordx2 v[150:151], v[102:103], off
	v_lshl_add_u64 v[100:101], v[100:101], 0, v[106:107]
	v_lshl_add_u64 v[102:103], v[102:103], 0, v[108:109]
	v_cvt_pk_bf16_f32 v16, v6, v7
	global_store_dword v[104:105], v16, off
	v_lshl_add_u64 v[104:105], v[104:105], 0, v[110:111]
	s_waitcnt vmcnt(22)
	v_pk_fma_f32 v[6:7], v[6:7], v[122:123], v[120:121]
	global_load_dwordx2 v[120:121], v[100:101], off
	global_load_dwordx2 v[122:123], v[102:103], off
	v_lshl_add_u64 v[100:101], v[100:101], 0, v[106:107]
	v_lshl_add_u64 v[102:103], v[102:103], 0, v[108:109]
	v_cvt_pk_bf16_f32 v16, v6, v7
	global_store_dword v[104:105], v16, off
	v_lshl_add_u64 v[104:105], v[104:105], 0, v[110:111]
	s_waitcnt vmcnt(22)
; __device__ __forceinline__ unsigned cvt_pk_bf16(float lo, float hi) { unsigned r; asm volatile("v_cvt_pk_bf16_f32 %0, %1, %2" : "=v"(r) : "v"(lo), "v"(hi)); return r; }
; __device__ __forceinline__ void gla_g2(const Params& P, int tid, int G, int bid) {
;     ...
;     for (int slot = bid * 512 + tid; slot < 16 * 8192; slot += G * 512) {
;         const int seq = slot >> 13, el = (slot & 8191) * 2, d = el & 127, dir = seq & 1;
;         float s0 = 0.f, s1 = 0.f;
; #pragma unroll 17
;         for (int p = 0; p < NCH; ++p) {
;             const int id = dir == 0 ? p : (p < 4 ? 3 - p : 71 - p);
;             const size_t base = ((size_t)seq * NCH + id);
;             *(unsigned*)(S + base * 16384 + el) = cvt_pk_bf16(s0, s1);
;             const f32x2 u = *(const f32x2*)(U + base * 16384 + el), dd = *(const f32x2*)(Dv + base * 128 + d);
;             s0 = dd.x * s0 + u.x; s1 = dd.y * s1 + u.y;
;         }
	v_pk_fma_f32 v[6:7], v[6:7], v[126:127], v[124:125]
	global_load_dwordx2 v[124:125], v[100:101], off
	global_load_dwordx2 v[126:127], v[102:103], off
	v_lshl_add_u64 v[100:101], v[100:101], 0, v[106:107]
	v_lshl_add_u64 v[102:103], v[102:103], 0, v[108:109]
	v_cvt_pk_bf16_f32 v16, v6, v7
	global_store_dword v[104:105], v16, off
	v_lshl_add_u64 v[104:105], v[104:105], 0, v[110:111]
	s_waitcnt vmcnt(22)
	v_pk_fma_f32 v[6:7], v[6:7], v[130:131], v[128:129]
	global_load_dwordx2 v[128:129], v[100:101], off
	global_load_dwordx2 v[130:131], v[102:103], off
	v_lshl_add_u64 v[100:101], v[100:101], 0, v[106:107]
	v_lshl_add_u64 v[102:103], v[102:103], 0, v[108:109]
	v_cvt_pk_bf16_f32 v16, v6, v7
	global_store_dword v[104:105], v16, off
	v_lshl_add_u64 v[104:105], v[104:105], 0, v[110:111]
	s_waitcnt vmcnt(22)
	v_pk_fma_f32 v[6:7], v[6:7], v[134:135], v[132:133]
	global_load_dwordx2 v[132:133], v[100:101], off
	global_load_dwordx2 v[134:135], v[102:103], off
	v_lshl_add_u64 v[100:101], v[100:101], 0, v[106:107]
	v_lshl_add_u64 v[102:103], v[102:103], 0, v[108:109]
	v_cvt_pk_bf16_f32 v16, v6, v7
	global_store_dword v[104:105], v16, off
	v_lshl_add_u64 v[104:105], v[104:105], 0, v[110:111]
	s_waitcnt vmcnt(22)
	v_pk_fma_f32 v[6:7], v[6:7], v[138:139], v[136:137]
	global_load_dwordx2 v[136:137], v[100:101], off
	global_load_dwordx2 v[138:139], v[102:103], off
	v_lshl_add_u64 v[100:101], v[100:101], 0, v[106:107]
	v_lshl_add_u64 v[102:103], v[102:103], 0, v[108:109]
	v_cvt_pk_bf16_f32 v16, v6, v7
	global_store_dword v[104:105], v16, off
	v_lshl_add_u64 v[104:105], v[104:105], 0, v[110:111]
	s_waitcnt vmcnt(22)
	v_pk_fma_f32 v[6:7], v[6:7], v[142:143], v[140:141]
	global_load_dwordx2 v[140:141], v[100:101], off
	global_load_dwordx2 v[142:143], v[102:103], off
	v_lshl_add_u64 v[100:101], v[100:101], 0, v[106:107]
	v_lshl_add_u64 v[102:103], v[102:103], 0, v[108:109]
	v_cvt_pk_bf16_f32 v16, v6, v7
	global_store_dword v[104:105], v16, off
	v_lshl_add_u64 v[104:105], v[104:105], 0, v[110:111]
	s_waitcnt vmcnt(22)
	v_pk_fma_f32 v[6:7], v[6:7], v[146:147], v[144:145]
	global_load_dwordx2 v[144:145], v[100:101], off
	global_load_dwordx2 v[146:147], v[102:103], off
	v_lshl_add_u64 v[100:101], v[100:101], 0, v[106:107]
	v_lshl_add_u64 v[102:103], v[102:103], 0, v[108:109]
	v_cvt_pk_bf16_f32 v16, v6, v7
	global_store_dword v[104:105], v16, off
	v_lshl_add_u64 v[104:105], v[104:105], 0, v[110:111]
	s_waitcnt vmcnt(22)
	v_pk_fma_f32 v[6:7], v[6:7], v[150:151], v[148:149]
	global_load_dwordx2 v[148:149], v[100:101], off
	global_load_dwordx2 v[150:151], v[102:103], off
	v_lshl_add_u64 v[100:101], v[100:101], 0, v[106:107]
	v_lshl_add_u64 v[102:103], v[102:103], 0, v[108:109]
	v_cvt_pk_bf16_f32 v16, v6, v7
	global_store_dword v[104:105], v16, off
	v_lshl_add_u64 v[104:105], v[104:105], 0, v[110:111]
	s_waitcnt vmcnt(22)
	v_pk_fma_f32 v[6:7], v[6:7], v[122:123], v[120:121]
	global_load_dwordx2 v[120:121], v[100:101], off
	global_load_dwordx2 v[122:123], v[102:103], off
	v_lshl_add_u64 v[100:101], v[100:101], 0, v[106:107]
	v_lshl_add_u64 v[102:103], v[102:103], 0, v[108:109]
	v_cvt_pk_bf16_f32 v16, v6, v7
	global_store_dword v[104:105], v16, off
	v_lshl_add_u64 v[104:105], v[104:105], 0, v[110:111]
	s_waitcnt vmcnt(22)
	v_pk_fma_f32 v[6:7], v[6:7], v[126:127], v[124:125]
	global_load_dwordx2 v[124:125], v[100:101], off
	global_load_dwordx2 v[126:127], v[102:103], off
	v_lshl_add_u64 v[100:101], v[100:101], 0, v[106:107]
	v_lshl_add_u64 v[102:103], v[102:103], 0, v[108:109]
	v_cvt_pk_bf16_f32 v16, v6, v7
	global_store_dword v[104:105], v16, off
	v_lshl_add_u64 v[104:105], v[104:105], 0, v[110:111]
	s_waitcnt vmcnt(22)
	v_pk_fma_f32 v[6:7], v[6:7], v[130:131], v[128:129]
	global_load_dwordx2 v[128:129], v[100:101], off
	global_load_dwordx2 v[130:131], v[102:103], off
	v_lshl_add_u64 v[100:101], v[100:101], 0, v[106:107]
	v_lshl_add_u64 v[102:103], v[102:103], 0, v[108:109]
	v_cvt_pk_bf16_f32 v16, v6, v7
	global_store_dword v[104:105], v16, off
	v_lshl_add_u64 v[104:105], v[104:105], 0, v[110:111]
	s_waitcnt vmcnt(22)
	v_pk_fma_f32 v[6:7], v[6:7], v[134:135], v[132:133]
	global_load_dwordx2 v[132:133], v[100:101], off
	global_load_dwordx2 v[134:135], v[102:103], off
	v_lshl_add_u64 v[100:101], v[100:101], 0, v[106:107]
	v_lshl_add_u64 v[102:103], v[102:103], 0, v[108:109]
	v_cvt_pk_bf16_f32 v16, v6, v7
	global_store_dword v[104:105], v16, off
	v_lshl_add_u64 v[104:105], v[104:105], 0, v[110:111]
	s_waitcnt vmcnt(22)
	v_pk_fma_f32 v[6:7], v[6:7], v[138:139], v[136:137]
	global_load_dwordx2 v[136:137], v[100:101], off
	global_load_dwordx2 v[138:139], v[102:103], off
	v_lshl_add_u64 v[100:101], v[100:101], 0, v[106:107]
	v_lshl_add_u64 v[102:103], v[102:103], 0, v[108:109]
	v_cvt_pk_bf16_f32 v16, v6, v7
	global_store_dword v[104:105], v16, off
	v_lshl_add_u64 v[104:105], v[104:105], 0, v[110:111]
	s_waitcnt vmcnt(22)
	v_pk_fma_f32 v[6:7], v[6:7], v[142:143], v[140:141]
	global_load_dwordx2 v[140:141], v[100:101], off
	global_load_dwordx2 v[142:143], v[102:103], off
	v_lshl_add_u64 v[100:101], v[100:101], 0, v[106:107]
	v_lshl_add_u64 v[102:103], v[102:103], 0, v[108:109]
	v_cvt_pk_bf16_f32 v16, v6, v7
	global_store_dword v[104:105], v16, off
	v_lshl_add_u64 v[104:105], v[104:105], 0, v[110:111]
	s_waitcnt vmcnt(22)
	v_pk_fma_f32 v[6:7], v[6:7], v[146:147], v[144:145]
	global_load_dwordx2 v[144:145], v[100:101], off
	global_load_dwordx2 v[146:147], v[102:103], off
	v_lshl_add_u64 v[100:101], v[100:101], 0, v[106:107]
	v_lshl_add_u64 v[102:103], v[102:103], 0, v[108:109]
	v_cvt_pk_bf16_f32 v16, v6, v7
	global_store_dword v[104:105], v16, off
	v_lshl_add_u64 v[104:105], v[104:105], 0, v[110:111]
	s_waitcnt vmcnt(22)
; __device__ __forceinline__ unsigned cvt_pk_bf16(float lo, float hi) { unsigned r; asm volatile("v_cvt_pk_bf16_f32 %0, %1, %2" : "=v"(r) : "v"(lo), "v"(hi)); return r; }
; __device__ __forceinline__ void gla_g2(const Params& P, int tid, int G, int bid) {
;     ...
;     for (int slot = bid * 512 + tid; slot < 16 * 8192; slot += G * 512) {
;         const int seq = slot >> 13, el = (slot & 8191) * 2, d = el & 127, dir = seq & 1;
;         float s0 = 0.f, s1 = 0.f;
; #pragma unroll 17
;         for (int p = 0; p < NCH; ++p) {
;             const int id = dir == 0 ? p : (p < 4 ? 3 - p : 71 - p);
;             const size_t base = ((size_t)seq * NCH + id);
;             *(unsigned*)(S + base * 16384 + el) = cvt_pk_bf16(s0, s1);
;             const f32x2 u = *(const f32x2*)(U + base * 16384 + el), dd = *(const f32x2*)(Dv + base * 128 + d);
;             s0 = dd.x * s0 + u.x; s1 = dd.y * s1 + u.y;
;         }
	v_pk_fma_f32 v[6:7], v[6:7], v[150:151], v[148:149]
	global_load_dwordx2 v[148:149], v[100:101], off
	global_load_dwordx2 v[150:151], v[102:103], off
	v_lshl_add_u64 v[100:101], v[100:101], 0, v[106:107]
	v_lshl_add_u64 v[102:103], v[102:103], 0, v[108:109]
	v_cvt_pk_bf16_f32 v16, v6, v7
	global_store_dword v[104:105], v16, off
	v_lshl_add_u64 v[104:105], v[104:105], 0, v[110:111]
	s_waitcnt vmcnt(22)
	v_pk_fma_f32 v[6:7], v[6:7], v[122:123], v[120:121]
	global_load_dwordx2 v[120:121], v[100:101], off
	global_load_dwordx2 v[122:123], v[102:103], off
	v_lshl_add_u64 v[100:101], v[100:101], 0, v[106:107]
	v_lshl_add_u64 v[102:103], v[102:103], 0, v[108:109]
	v_cvt_pk_bf16_f32 v16, v6, v7
	global_store_dword v[104:105], v16, off
	v_lshl_add_u64 v[104:105], v[104:105], 0, v[110:111]
	s_waitcnt vmcnt(22)
	v_pk_fma_f32 v[6:7], v[6:7], v[126:127], v[124:125]
	global_load_dwordx2 v[124:125], v[100:101], off
	global_load_dwordx2 v[126:127], v[102:103], off
	v_lshl_add_u64 v[100:101], v[100:101], 0, v[106:107]
	v_lshl_add_u64 v[102:103], v[102:103], 0, v[108:109]
	v_cvt_pk_bf16_f32 v16, v6, v7
	global_store_dword v[104:105], v16, off
	v_lshl_add_u64 v[104:105], v[104:105], 0, v[110:111]
	s_waitcnt vmcnt(22)
	v_pk_fma_f32 v[6:7], v[6:7], v[130:131], v[128:129]
	global_load_dwordx2 v[128:129], v[100:101], off
	global_load_dwordx2 v[130:131], v[102:103], off
	v_lshl_add_u64 v[100:101], v[100:101], 0, v[106:107]
	v_lshl_add_u64 v[102:103], v[102:103], 0, v[108:109]
	v_cvt_pk_bf16_f32 v16, v6, v7
	global_store_dword v[104:105], v16, off
	v_lshl_add_u64 v[104:105], v[104:105], 0, v[110:111]
	s_waitcnt vmcnt(22)
	v_pk_fma_f32 v[6:7], v[6:7], v[134:135], v[132:133]
	global_load_dwordx2 v[132:133], v[100:101], off
	global_load_dwordx2 v[134:135], v[102:103], off
	v_lshl_add_u64 v[100:101], v[100:101], 0, v[106:107]
	v_lshl_add_u64 v[102:103], v[102:103], 0, v[108:109]
	v_cvt_pk_bf16_f32 v16, v6, v7
	global_store_dword v[104:105], v16, off
	v_lshl_add_u64 v[104:105], v[104:105], 0, v[110:111]
	s_waitcnt vmcnt(22)
	v_pk_fma_f32 v[6:7], v[6:7], v[138:139], v[136:137]
	global_load_dwordx2 v[136:137], v[100:101], off
	global_load_dwordx2 v[138:139], v[102:103], off
	v_lshl_add_u64 v[100:101], v[100:101], 0, v[106:107]
	v_lshl_add_u64 v[102:103], v[102:103], 0, v[108:109]
	v_cvt_pk_bf16_f32 v16, v6, v7
	global_store_dword v[104:105], v16, off
	v_lshl_add_u64 v[104:105], v[104:105], 0, v[110:111]
	s_waitcnt vmcnt(22)
	v_pk_fma_f32 v[6:7], v[6:7], v[142:143], v[140:141]
	global_load_dwordx2 v[140:141], v[100:101], off
	global_load_dwordx2 v[142:143], v[102:103], off
	v_lshl_add_u64 v[100:101], v[100:101], 0, v[106:107]
	v_lshl_add_u64 v[102:103], v[102:103], 0, v[108:109]
	v_cvt_pk_bf16_f32 v16, v6, v7
	global_store_dword v[104:105], v16, off
	v_lshl_add_u64 v[104:105], v[104:105], 0, v[110:111]
	s_waitcnt vmcnt(22)
	v_pk_fma_f32 v[6:7], v[6:7], v[146:147], v[144:145]
	global_load_dwordx2 v[144:145], v[100:101], off
	global_load_dwordx2 v[146:147], v[102:103], off
	v_lshl_add_u64 v[100:101], v[100:101], 0, v[106:107]
	v_lshl_add_u64 v[102:103], v[102:103], 0, v[108:109]
	v_cvt_pk_bf16_f32 v16, v6, v7
	global_store_dword v[104:105], v16, off
	v_lshl_add_u64 v[104:105], v[104:105], 0, v[110:111]
	s_waitcnt vmcnt(22)
	v_pk_fma_f32 v[6:7], v[6:7], v[150:151], v[148:149]
	global_load_dwordx2 v[148:149], v[100:101], off
	global_load_dwordx2 v[150:151], v[102:103], off
	v_lshl_add_u64 v[100:101], v[100:101], 0, v[106:107]
	v_lshl_add_u64 v[102:103], v[102:103], 0, v[108:109]
	v_cvt_pk_bf16_f32 v16, v6, v7
	global_store_dword v[104:105], v16, off
	v_lshl_add_u64 v[104:105], v[104:105], 0, v[110:111]
	s_waitcnt vmcnt(22)
	v_pk_fma_f32 v[6:7], v[6:7], v[122:123], v[120:121]
	global_load_dwordx2 v[120:121], v[100:101], off
	global_load_dwordx2 v[122:123], v[102:103], off
	v_lshl_add_u64 v[100:101], v[100:101], 0, v[106:107]
	v_lshl_add_u64 v[102:103], v[102:103], 0, v[108:109]
	v_cvt_pk_bf16_f32 v16, v6, v7
	global_store_dword v[104:105], v16, off
	v_lshl_add_u64 v[104:105], v[104:105], 0, v[110:111]
	s_waitcnt vmcnt(22)
	v_pk_fma_f32 v[6:7], v[6:7], v[126:127], v[124:125]
	global_load_dwordx2 v[124:125], v[100:101], off
	global_load_dwordx2 v[126:127], v[102:103], off
	v_lshl_add_u64 v[100:101], v[100:101], 0, v[106:107]
	v_lshl_add_u64 v[102:103], v[102:103], 0, v[108:109]
	v_cvt_pk_bf16_f32 v16, v6, v7
	global_store_dword v[104:105], v16, off
	v_lshl_add_u64 v[104:105], v[104:105], 0, v[110:111]
	s_waitcnt vmcnt(22)
	v_pk_fma_f32 v[6:7], v[6:7], v[130:131], v[128:129]
	global_load_dwordx2 v[128:129], v[100:101], off
	global_load_dwordx2 v[130:131], v[102:103], off
	v_lshl_add_u64 v[100:101], v[100:101], 0, v[106:107]
	v_lshl_add_u64 v[102:103], v[102:103], 0, v[108:109]
	v_cvt_pk_bf16_f32 v16, v6, v7
	global_store_dword v[104:105], v16, off
	v_lshl_add_u64 v[104:105], v[104:105], 0, v[110:111]
	s_waitcnt vmcnt(22)
	v_pk_fma_f32 v[6:7], v[6:7], v[134:135], v[132:133]
	global_load_dwordx2 v[132:133], v[100:101], off
	global_load_dwordx2 v[134:135], v[102:103], off
	v_cvt_pk_bf16_f32 v16, v6, v7
	global_store_dword v[104:105], v16, off
	v_lshl_add_u64 v[104:105], v[104:105], 0, v[110:111]
	s_waitcnt vmcnt(22)
	v_pk_fma_f32 v[6:7], v[6:7], v[138:139], v[136:137]
	v_cvt_pk_bf16_f32 v16, v6, v7
	global_store_dword v[104:105], v16, off
	v_lshl_add_u64 v[104:105], v[104:105], 0, v[110:111]
	s_waitcnt vmcnt(20)
	v_pk_fma_f32 v[6:7], v[6:7], v[142:143], v[140:141]
	v_cvt_pk_bf16_f32 v16, v6, v7
	global_store_dword v[104:105], v16, off
	v_lshl_add_u64 v[104:105], v[104:105], 0, v[110:111]
	s_waitcnt vmcnt(18)
	v_pk_fma_f32 v[6:7], v[6:7], v[146:147], v[144:145]
	v_cvt_pk_bf16_f32 v16, v6, v7
	global_store_dword v[104:105], v16, off
	v_lshl_add_u64 v[104:105], v[104:105], 0, v[110:111]
	s_waitcnt vmcnt(16)
	v_pk_fma_f32 v[6:7], v[6:7], v[150:151], v[148:149]
	v_cvt_pk_bf16_f32 v16, v6, v7
	global_store_dword v[104:105], v16, off
	v_lshl_add_u64 v[104:105], v[104:105], 0, v[110:111]
	s_waitcnt vmcnt(14)
	v_pk_fma_f32 v[6:7], v[6:7], v[122:123], v[120:121]
	v_cvt_pk_bf16_f32 v16, v6, v7
	global_store_dword v[104:105], v16, off
	v_lshl_add_u64 v[104:105], v[104:105], 0, v[110:111]
	s_waitcnt vmcnt(12)
	v_pk_fma_f32 v[6:7], v[6:7], v[126:127], v[124:125]
	v_cvt_pk_bf16_f32 v16, v6, v7
	global_store_dword v[104:105], v16, off
	v_lshl_add_u64 v[104:105], v[104:105], 0, v[110:111]
	s_waitcnt vmcnt(10)
	v_pk_fma_f32 v[6:7], v[6:7], v[130:131], v[128:129]
	v_cvt_pk_bf16_f32 v16, v6, v7
	global_store_dword v[104:105], v16, off
	s_waitcnt vmcnt(8)
	v_pk_fma_f32 v[6:7], v[6:7], v[134:135], v[132:133]
	v_add_u32_e32 v10, s10, v10
	s_mov_b32 s17, 0x1ffff
	v_cmp_lt_i32_e32 vcc, s17, v10
	s_or_b64 s[50:51], vcc, s[50:51]
	s_andn2_b64 exec, exec, s[50:51]
	s_cbranch_execnz .LBB0_829
